# combo12 + K-loop headers aligned to 64 bytes (second measurement of the same bytes)
# speedup vs baseline: 1.0028x; 1.0028x over previous
; template <class Epi, class Sched, bool ALIGN_EPI = false, bool SP2 = false, bool ACHUNK = false>
; __device__ __forceinline__ void gemm_phase(PG8_LAS unsigned char* lds, const Gemm g, const Sched& S, const Epi& E) {
;     ...
;         const bool has_next = S.next(ui + 1, nxt);
;         const char* nA = has_next ? (const char*)g.A + (size_t)nxt.pm * tstepA : cA; const char* nB = has_next ? (const char*)g.Bt + (size_t)nxt.pn * tstepB : cB;
;         for (int t = 0; t < nt; t += 2) {
;             const bool last = (t == nt - 2);
.LBB0_51:
	s_add_u32 s20, s20, 0x80
	s_addc_u32 s21, s21, 0
	s_add_u32 s44, s18, 0x100
	s_addc_u32 s45, s19, 0
	s_mov_b32 s18, 0
	.p2align	6

; #define PG8_STAGE(bufoff, gbase, voff) do { _Pragma("unroll") for (int _i = 0; _i < 2; ++_i) \
;         __builtin_amdgcn_global_load_lds((const unsigned*)((const char*)(gbase) + (voff)[_i]), (PG8_LAS unsigned*)(lds + (bufoff) + ldsw + _i * 8192), 16, 0, 0); } while (0)
; #define PG8_LDA(dst, b, h) do { _Pragma("unroll") for (int m = 0; m < 4; ++m) _Pragma("unroll") for (int k = 0; k < 2; ++k) dst[m][k] = *(const PG8_LAS bf16x8*)(lds + PG8_SA(b, h) + aoff + m * 2048 + k * 1024); } while (0)
; #define PG8_LDB(dst, b, h) do { _Pragma("unroll") for (int n = 0; n < 2; ++n) _Pragma("unroll") for (int k = 0; k < 2; ++k) dst[n][k] = *(const PG8_LAS bf16x8*)(lds + PG8_SB(b, h) + boff + n * 2048 + k * 1024); } while (0)
; #define PG8_WAIT_V(n) asm volatile("s_waitcnt vmcnt(" #n ")" ::: "memory")
; #define PG8_WAIT_L(n) asm volatile("s_waitcnt lgkmcnt(" #n ")" ::: "memory")
; template <class Epi, class Sched, bool ALIGN_EPI = false, bool SP2 = false, bool ACHUNK = false>
; __device__ __forceinline__ void gemm_phase(PG8_LAS unsigned char* lds, const Gemm g, const Sched& S, const Epi& E) {
;     ...
;         const bool has_next = S.next(ui + 1, nxt);
;         const char* nA = has_next ? (const char*)g.A + (size_t)nxt.pm * tstepA : cA; const char* nB = has_next ? (const char*)g.Bt + (size_t)nxt.pn * tstepB : cB;
;         for (int t = 0; t < nt; t += 2) {
;             const bool last = (t == nt - 2);
;             if constexpr (Epi::HAS_MID) { if (t == Epi::MID_T) E.mid(acc, cur, wr, wc, fr, fq, ShflDev{}); }
;             const char* a1 = cA + (size_t)(t + 1) * kstep;
;             const char* a2 = last ? nA : cA + (size_t)(t + 2) * kstep; const char* b2 = last ? nB : cB + (size_t)(t + 2) * kstep;
;             const char* a3 = a2 + kstep; const char* b3 = b2 + kstep;
;             if (last && has_next) S.a_ready(nxt);
;             if constexpr (SP2) {
;             PG8_LDB(B0, 0, 0); PG8_LDB(B1, 0, 1); PG8_SCHED; PG8_LDA(At, 0, 0); PG8_STAGE(PG8_SA(1, 1), a1 + hstepA, voffA);
;             PG8_WAIT_V(8); PG8_WAIT_L(0); PG8_BAR; PG8_MMA(0, 0, At, B0); PG8_MMA(0, 1, At, B1); PG8_BAR; PG8_SCHED;
;             PG8_LDA(At, 0, 1); PG8_STAGE(PG8_SB(0, 0), b2, voffB); PG8_STAGE(PG8_SB(0, 1), b2 + hstepB, voffB); PG8_STAGE(PG8_SA(0, 0), a2, voffA);
;             PG8_WAIT_V(8); PG8_WAIT_L(0); PG8_BAR; PG8_MMA(1, 0, At, B0); PG8_MMA(1, 1, At, B1); PG8_BAR; PG8_SCHED;
.LBB0_106:
	s_andn2_b64 vcc, exec, s[44:45]
	s_nop 0
	s_cbranch_vccnz .LBB0_110
	s_add_u32 s8, s4, 0x100
	s_addc_u32 s9, s5, 0
	s_add_u32 s0, s6, 0x80
	s_addc_u32 s1, s7, 0
	s_mov_b32 s4, 0
	s_add_i32 s6, s4, 2
	s_add_u32 s7, s0, 0x80
	s_addc_u32 s5, s1, 0
	s_add_i32 s77, 0, 0x10000
	s_cmp_eq_u32 s54, s4
	s_cselect_b32 s5, s49, s5
	s_cselect_b32 s4, s48, s7
	v_add_u32_e32 v2, s77, v224
	s_cselect_b32 s79, s51, s9
	s_cselect_b32 s78, s50, s8
	s_add_i32 s7, 0, 0x14000
	s_waitcnt lgkmcnt(0)
	ds_read_b128 v[36:39], v2
	ds_read_b128 v[40:43], v2 offset:1024
	ds_read_b128 v[44:47], v2 offset:2048
	ds_read_b128 v[48:51], v2 offset:3072
	v_add_u32_e32 v2, s7, v224
	ds_read_b128 v[52:55], v2
	ds_read_b128 v[56:59], v2 offset:1024
	ds_read_b128 v[60:63], v2 offset:2048
	ds_read_b128 v[64:67], v2 offset:3072
	s_add_u32 s98, s0, s28
	s_addc_u32 s99, s1, s29
	s_add_i32 m0, s25, 0xc000
	ds_read_b128 v[164:167], v238
	ds_read_b128 v[168:171], v238 offset:1024
	ds_read_b128 v[184:187], v238 offset:2048
	ds_read_b128 v[188:191], v238 offset:3072
	ds_read_b128 v[198:201], v238 offset:4096
	ds_read_b128 v[202:205], v238 offset:5120
	ds_read_b128 v[206:209], v238 offset:6144
	ds_read_b128 v[210:213], v238 offset:7168
	global_load_lds_dwordx4 v172, s[98:99]
	s_add_i32 m0, s25, 0xe000
	s_nop 0
	global_load_lds_dwordx4 v176, s[98:99]
	s_waitcnt vmcnt(8)
	s_waitcnt lgkmcnt(0)
	s_barrier
	s_setprio 1
	v_mfma_f32_16x16x32_bf16 v[148:151], v[36:39], v[164:167], 0
	v_mfma_f32_16x16x32_bf16 v[152:155], v[44:47], v[164:167], 0
	v_mfma_f32_16x16x32_bf16 v[132:135], v[36:39], v[184:187], 0
	v_mfma_f32_16x16x32_bf16 v[140:143], v[44:47], v[184:187], 0
	v_mfma_f32_16x16x32_bf16 v[136:139], v[36:39], v[198:201], 0
	v_mfma_f32_16x16x32_bf16 v[144:147], v[44:47], v[198:201], 0
	v_mfma_f32_16x16x32_bf16 v[160:163], v[36:39], v[206:209], 0
	v_mfma_f32_16x16x32_bf16 v[156:159], v[44:47], v[206:209], 0
	v_mfma_f32_16x16x32_bf16 v[148:151], v[40:43], v[168:171], v[148:151]
	v_mfma_f32_16x16x32_bf16 v[152:155], v[48:51], v[168:171], v[152:155]
	v_mfma_f32_16x16x32_bf16 v[132:135], v[40:43], v[188:191], v[132:135]
	v_mfma_f32_16x16x32_bf16 v[140:143], v[48:51], v[188:191], v[140:143]
	v_mfma_f32_16x16x32_bf16 v[136:139], v[40:43], v[202:205], v[136:139]
	v_mfma_f32_16x16x32_bf16 v[144:147], v[48:51], v[202:205], v[144:147]
	v_mfma_f32_16x16x32_bf16 v[160:163], v[40:43], v[210:213], v[160:163]
	v_mfma_f32_16x16x32_bf16 v[156:159], v[48:51], v[210:213], v[156:159]
	s_setprio 0
	s_setprio 1
	v_mfma_f32_16x16x32_bf16 v[124:127], v[52:55], v[164:167], 0
	v_mfma_f32_16x16x32_bf16 v[128:131], v[60:63], v[164:167], 0
	v_mfma_f32_16x16x32_bf16 v[116:119], v[52:55], v[184:187], 0
	v_mfma_f32_16x16x32_bf16 v[120:123], v[60:63], v[184:187], 0
	v_mfma_f32_16x16x32_bf16 v[112:115], v[52:55], v[198:201], 0
	v_mfma_f32_16x16x32_bf16 v[108:111], v[60:63], v[198:201], 0
	v_mfma_f32_16x16x32_bf16 v[104:107], v[52:55], v[206:209], 0
	v_mfma_f32_16x16x32_bf16 v[100:103], v[60:63], v[206:209], 0
	v_mfma_f32_16x16x32_bf16 v[124:127], v[56:59], v[168:171], v[124:127]
	v_mfma_f32_16x16x32_bf16 v[128:131], v[64:67], v[168:171], v[128:131]
	v_mfma_f32_16x16x32_bf16 v[116:119], v[56:59], v[188:191], v[116:119]
	v_mfma_f32_16x16x32_bf16 v[120:123], v[64:67], v[188:191], v[120:123]
	v_mfma_f32_16x16x32_bf16 v[112:115], v[56:59], v[202:205], v[112:115]
	v_mfma_f32_16x16x32_bf16 v[108:111], v[64:67], v[202:205], v[108:111]
	v_mfma_f32_16x16x32_bf16 v[104:107], v[56:59], v[210:213], v[104:107]
	v_mfma_f32_16x16x32_bf16 v[100:103], v[64:67], v[210:213], v[100:103]
	s_setprio 0
	s_barrier
	s_add_i32 s77, s77, s17
	s_add_u32 s98, s78, s18
	s_addc_u32 s99, s79, s19
	s_mov_b32 m0, s77
	ds_read_b128 v[164:167], v238 offset:16384
	ds_read_b128 v[168:171], v238 offset:17408
	ds_read_b128 v[184:187], v238 offset:18432
	ds_read_b128 v[188:191], v238 offset:19456
	ds_read_b128 v[198:201], v238 offset:20480
	ds_read_b128 v[202:205], v238 offset:21504
	ds_read_b128 v[206:209], v238 offset:22528
	ds_read_b128 v[210:213], v238 offset:23552
	global_load_lds_dwordx4 v174, s[78:79]
	s_add_i32 m0, s77, 0x2000
	s_add_i32 s7, s7, s17
	global_load_lds_dwordx4 v178, s[78:79]
	s_mov_b32 m0, s7
	s_nop 0
	global_load_lds_dwordx4 v174, s[98:99]
	s_add_i32 m0, s7, 0x2000
	s_nop 0
	global_load_lds_dwordx4 v178, s[98:99]
	s_mov_b32 m0, s25
	s_nop 0
	global_load_lds_dwordx4 v172, s[4:5]
	s_mov_b32 m0, s26
	s_nop 0
	global_load_lds_dwordx4 v176, s[4:5]
	s_waitcnt vmcnt(8)
	s_waitcnt lgkmcnt(0)
	s_barrier
	s_setprio 1
	v_mfma_f32_16x16x32_bf16 v[96:99], v[36:39], v[164:167], 0
	v_mfma_f32_16x16x32_bf16 v[92:95], v[44:47], v[164:167], 0
	v_mfma_f32_16x16x32_bf16 v[88:91], v[36:39], v[184:187], 0
	v_mfma_f32_16x16x32_bf16 v[84:87], v[44:47], v[184:187], 0
	v_mfma_f32_16x16x32_bf16 v[80:83], v[36:39], v[198:201], 0
	v_mfma_f32_16x16x32_bf16 v[76:79], v[44:47], v[198:201], 0
	v_mfma_f32_16x16x32_bf16 v[36:39], v[36:39], v[206:209], 0
	v_mfma_f32_16x16x32_bf16 v[96:99], v[40:43], v[168:171], v[96:99]
	v_mfma_f32_16x16x32_bf16 v[92:95], v[48:51], v[168:171], v[92:95]
	v_mfma_f32_16x16x32_bf16 v[88:91], v[40:43], v[188:191], v[88:91]
	v_mfma_f32_16x16x32_bf16 v[84:87], v[48:51], v[188:191], v[84:87]
	v_mfma_f32_16x16x32_bf16 v[80:83], v[40:43], v[202:205], v[80:83]
	v_mfma_f32_16x16x32_bf16 v[76:79], v[48:51], v[202:205], v[76:79]
	v_mfma_f32_16x16x32_bf16 v[36:39], v[40:43], v[210:213], v[36:39]
	v_mfma_f32_16x16x32_bf16 v[40:43], v[44:47], v[206:209], 0
	v_mfma_f32_16x16x32_bf16 v[40:43], v[48:51], v[210:213], v[40:43]
	s_setprio 0
	s_setprio 1
	v_mfma_f32_16x16x32_bf16 v[28:31], v[52:55], v[164:167], 0
	v_mfma_f32_16x16x32_bf16 v[32:35], v[60:63], v[164:167], 0
	v_mfma_f32_16x16x32_bf16 v[20:23], v[52:55], v[184:187], 0
	v_mfma_f32_16x16x32_bf16 v[24:27], v[60:63], v[184:187], 0
	v_mfma_f32_16x16x32_bf16 v[16:19], v[52:55], v[198:201], 0
	v_mfma_f32_16x16x32_bf16 v[12:15], v[60:63], v[198:201], 0
	v_mfma_f32_16x16x32_bf16 v[8:11], v[52:55], v[206:209], 0
	v_mfma_f32_16x16x32_bf16 v[4:7], v[60:63], v[206:209], 0
	v_mfma_f32_16x16x32_bf16 v[28:31], v[56:59], v[168:171], v[28:31]
	v_mfma_f32_16x16x32_bf16 v[32:35], v[64:67], v[168:171], v[32:35]
	v_mfma_f32_16x16x32_bf16 v[20:23], v[56:59], v[188:191], v[20:23]
	v_mfma_f32_16x16x32_bf16 v[24:27], v[64:67], v[188:191], v[24:27]
	v_mfma_f32_16x16x32_bf16 v[16:19], v[56:59], v[202:205], v[16:19]
	v_mfma_f32_16x16x32_bf16 v[12:15], v[64:67], v[202:205], v[12:15]
	v_mfma_f32_16x16x32_bf16 v[8:11], v[56:59], v[210:213], v[8:11]
	v_mfma_f32_16x16x32_bf16 v[4:7], v[64:67], v[210:213], v[4:7]
	s_setprio 0
	s_barrier
	s_branch .Lpe_join_108
	.p2align	6

; template <class Epi, class Sched, bool ALIGN_EPI = false, bool SP2 = false, bool ACHUNK = false>
; __device__ __forceinline__ void gemm_phase(PG8_LAS unsigned char* lds, const Gemm g, const Sched& S, const Epi& E) {
;     ...
;         const bool has_next = S.next(ui + 1, nxt);
;         const char* nA = has_next ? (const char*)g.A + (size_t)nxt.pm * tstepA : cA; const char* nB = has_next ? (const char*)g.Bt + (size_t)nxt.pn * tstepB : cB;
;         for (int t = 0; t < nt; t += 2) {
;             const bool last = (t == nt - 2);
.LBB0_215:
	s_add_u32 s48, s20, 0x100
	s_addc_u32 s49, s21, 0
	s_add_u32 s20, s22, 0x80
	s_addc_u32 s21, s23, 0
	s_mov_b32 s22, 0
	.p2align	6

.LBB0_267:
	v_mov_b32_e32 v2, v232
	v_mov_b32_e32 v4, v233
	s_mov_b32 s9, 0x8000
	v_lshl_add_u32 v4, v4, 3, s47
	v_add_u32_e32 v134, s48, v2
	v_ashrrev_i32_e32 v5, 31, v4
	v_ashrrev_i32_e32 v135, 31, v134
	v_lshl_add_u64 v[4:5], v[4:5], 1, s[76:77]
	v_lshlrev_b64 v[134:135], 11, v[134:135]
	v_lshl_add_u64 v[4:5], v[4:5], 0, v[134:135]
	global_load_dwordx4 v[214:217], v[4:5], off
	global_load_dwordx4 v[190:193], v[4:5], off offset:256
	v_add_co_u32_e32 v136, vcc, s9, v4
	s_mov_b64 s[52:53], 0x8000
	s_nop 0
	v_addc_co_u32_e32 v137, vcc, 0, v5, vcc
	v_lshl_add_u64 v[134:135], v[4:5], 0, s[52:53]
	global_load_dwordx4 v[186:189], v[136:137], off
	global_load_dwordx4 v[182:185], v[134:135], off offset:256
	s_mov_b32 s9, 0x10000
	v_add_co_u32_e32 v136, vcc, s9, v4
	s_mov_b64 s[52:53], 0x10000
	s_nop 0
	v_addc_co_u32_e32 v137, vcc, 0, v5, vcc
	v_lshl_add_u64 v[134:135], v[4:5], 0, s[52:53]
	global_load_dwordx4 v[178:181], v[136:137], off
	global_load_dwordx4 v[174:177], v[134:135], off offset:256
	s_mov_b32 s9, 0x18000
	v_add_co_u32_e32 v136, vcc, s9, v4
	s_mov_b64 s[52:53], 0x18000
	s_nop 0
	v_addc_co_u32_e32 v137, vcc, 0, v5, vcc
	v_lshl_add_u64 v[134:135], v[4:5], 0, s[52:53]
	global_load_dwordx4 v[170:173], v[136:137], off
	global_load_dwordx4 v[166:169], v[134:135], off offset:256
	s_mov_b32 s9, 0x40000
	v_add_co_u32_e32 v136, vcc, s9, v4
	s_mov_b64 s[52:53], 0x40000
	s_nop 0
	v_addc_co_u32_e32 v137, vcc, 0, v5, vcc
	v_lshl_add_u64 v[134:135], v[4:5], 0, s[52:53]
	global_load_dwordx4 v[162:165], v[136:137], off
	global_load_dwordx4 v[158:161], v[134:135], off offset:256
	s_mov_b32 s9, 0x48000
	v_add_co_u32_e32 v136, vcc, s9, v4
	s_mov_b64 s[52:53], 0x48000
	s_nop 0
	v_addc_co_u32_e32 v137, vcc, 0, v5, vcc
	v_lshl_add_u64 v[134:135], v[4:5], 0, s[52:53]
	global_load_dwordx4 v[154:157], v[136:137], off
	global_load_dwordx4 v[142:145], v[134:135], off offset:256
	s_mov_b32 s9, 0x50000
	s_mov_b64 s[52:53], 0x50000
	v_add_co_u32_e32 v136, vcc, s9, v4
	v_lshl_add_u64 v[134:135], v[4:5], 0, s[52:53]
	s_nop 0
	v_addc_co_u32_e32 v137, vcc, 0, v5, vcc
	global_load_dwordx4 v[146:149], v[136:137], off
	s_nop 0
	global_load_dwordx4 v[134:137], v[134:135], off offset:256
	s_mov_b64 s[52:53], 0x58000
	s_mov_b32 s9, 0x58000
	v_lshl_add_u64 v[138:139], v[4:5], 0, s[52:53]
	v_add_co_u32_e32 v4, vcc, s9, v4
	s_nop 1
	v_addc_co_u32_e32 v5, vcc, 0, v5, vcc
	global_load_dwordx4 v[150:153], v[4:5], off
	s_nop 0
	global_load_dwordx4 v[138:141], v[138:139], off offset:256
	s_waitcnt vmcnt(0)
	v_lshlrev_b32_e32 v4, 16, v214
	v_and_b32_e32 v5, 0xffff0000, v214
	v_pk_mul_f32 v[126:127], v[126:127], v[4:5]
	v_lshlrev_b32_e32 v4, 16, v216
	v_and_b32_e32 v5, 0xffff0000, v216
	v_pk_mul_f32 v[130:131], v[130:131], v[4:5]
	v_lshlrev_b32_e32 v4, 16, v190
	v_and_b32_e32 v5, 0xffff0000, v190
	v_pk_mul_f32 v[122:123], v[122:123], v[4:5]
	v_lshlrev_b32_e32 v4, 16, v192
	v_and_b32_e32 v5, 0xffff0000, v192
	v_pk_mul_f32 v[118:119], v[118:119], v[4:5]
	v_lshlrev_b32_e32 v4, 16, v186
	v_and_b32_e32 v5, 0xffff0000, v186
	v_pk_mul_f32 v[114:115], v[114:115], v[4:5]
	v_lshlrev_b32_e32 v4, 16, v188
	v_and_b32_e32 v5, 0xffff0000, v188
	v_pk_mul_f32 v[110:111], v[110:111], v[4:5]
	v_lshlrev_b32_e32 v4, 16, v182
	v_and_b32_e32 v5, 0xffff0000, v182
	v_pk_mul_f32 v[106:107], v[106:107], v[4:5]
	v_lshlrev_b32_e32 v4, 16, v184
	v_and_b32_e32 v5, 0xffff0000, v184
	v_pk_mul_f32 v[102:103], v[102:103], v[4:5]
	v_lshlrev_b32_e32 v4, 16, v178
	v_and_b32_e32 v5, 0xffff0000, v178
	v_pk_mul_f32 v[98:99], v[98:99], v[4:5]
	v_lshlrev_b32_e32 v4, 16, v180
	v_and_b32_e32 v5, 0xffff0000, v180
	v_pk_mul_f32 v[94:95], v[94:95], v[4:5]
	v_lshlrev_b32_e32 v4, 16, v174
	v_and_b32_e32 v5, 0xffff0000, v174
	v_pk_mul_f32 v[90:91], v[90:91], v[4:5]
	v_lshlrev_b32_e32 v4, 16, v176
	v_and_b32_e32 v5, 0xffff0000, v176
	v_pk_mul_f32 v[86:87], v[86:87], v[4:5]
	v_lshlrev_b32_e32 v4, 16, v170
	v_and_b32_e32 v5, 0xffff0000, v170
	v_pk_mul_f32 v[82:83], v[82:83], v[4:5]
	v_lshlrev_b32_e32 v4, 16, v172
	v_and_b32_e32 v5, 0xffff0000, v172
	v_pk_mul_f32 v[78:79], v[78:79], v[4:5]
	v_lshlrev_b32_e32 v4, 16, v166
	v_and_b32_e32 v5, 0xffff0000, v166
	v_pk_mul_f32 v[74:75], v[74:75], v[4:5]
	v_lshlrev_b32_e32 v4, 16, v168
	v_and_b32_e32 v5, 0xffff0000, v168
	v_pk_mul_f32 v[70:71], v[70:71], v[4:5]
	v_lshlrev_b32_e32 v4, 16, v162
	v_and_b32_e32 v5, 0xffff0000, v162
	v_pk_mul_f32 v[66:67], v[66:67], v[4:5]
	v_lshlrev_b32_e32 v4, 16, v164
	v_and_b32_e32 v5, 0xffff0000, v164
	v_pk_mul_f32 v[62:63], v[62:63], v[4:5]
	v_lshlrev_b32_e32 v4, 16, v158
	v_and_b32_e32 v5, 0xffff0000, v158
	v_pk_mul_f32 v[58:59], v[58:59], v[4:5]
	v_lshlrev_b32_e32 v4, 16, v160
	v_and_b32_e32 v5, 0xffff0000, v160
	v_pk_mul_f32 v[54:55], v[54:55], v[4:5]
	v_lshlrev_b32_e32 v4, 16, v154
	v_and_b32_e32 v5, 0xffff0000, v154
	v_pk_mul_f32 v[50:51], v[50:51], v[4:5]
	v_lshlrev_b32_e32 v4, 16, v156
	v_and_b32_e32 v5, 0xffff0000, v156
	v_pk_mul_f32 v[46:47], v[46:47], v[4:5]
	v_lshlrev_b32_e32 v4, 16, v142
	v_and_b32_e32 v5, 0xffff0000, v142
	v_pk_mul_f32 v[42:43], v[42:43], v[4:5]
	v_lshlrev_b32_e32 v4, 16, v144
	v_and_b32_e32 v5, 0xffff0000, v144
	v_pk_mul_f32 v[38:39], v[38:39], v[4:5]
	v_lshlrev_b32_e32 v4, 16, v146
	v_and_b32_e32 v5, 0xffff0000, v146
	v_pk_mul_f32 v[34:35], v[34:35], v[4:5]
	v_lshlrev_b32_e32 v4, 16, v148
	v_and_b32_e32 v5, 0xffff0000, v148
	v_pk_mul_f32 v[30:31], v[30:31], v[4:5]
	v_lshlrev_b32_e32 v4, 16, v134
	v_and_b32_e32 v5, 0xffff0000, v134
	v_lshlrev_b32_e32 v134, 16, v135
	v_and_b32_e32 v135, 0xffff0000, v135
	v_pk_mul_f32 v[28:29], v[28:29], v[134:135]
	v_pk_mul_f32 v[26:27], v[26:27], v[4:5]
	v_lshlrev_b32_e32 v4, 16, v136
	v_and_b32_e32 v5, 0xffff0000, v136
	v_lshlrev_b32_e32 v134, 16, v137
	v_and_b32_e32 v135, 0xffff0000, v137
	v_lshlrev_b32_e32 v142, 16, v143
	v_and_b32_e32 v143, 0xffff0000, v143
	v_pk_mul_f32 v[24:25], v[24:25], v[134:135]
	v_pk_mul_f32 v[22:23], v[22:23], v[4:5]
	v_lshlrev_b32_e32 v4, 16, v150
	v_and_b32_e32 v5, 0xffff0000, v150
	v_lshlrev_b32_e32 v134, 16, v151
	v_and_b32_e32 v135, 0xffff0000, v151
	v_pk_mul_f32 v[44:45], v[44:45], v[142:143]
	v_lshlrev_b32_e32 v142, 16, v145
	v_and_b32_e32 v143, 0xffff0000, v145
	v_pk_mul_f32 v[20:21], v[20:21], v[134:135]
	v_pk_mul_f32 v[18:19], v[18:19], v[4:5]
	v_lshlrev_b32_e32 v4, 16, v152
	v_and_b32_e32 v5, 0xffff0000, v152
	v_lshlrev_b32_e32 v134, 16, v153
	v_and_b32_e32 v135, 0xffff0000, v153
	v_lshlrev_b32_e32 v214, 16, v215
	v_and_b32_e32 v215, 0xffff0000, v215
	v_lshlrev_b32_e32 v190, 16, v191
	v_and_b32_e32 v191, 0xffff0000, v191
	v_lshlrev_b32_e32 v186, 16, v187
	v_and_b32_e32 v187, 0xffff0000, v187
	v_lshlrev_b32_e32 v182, 16, v183
	v_and_b32_e32 v183, 0xffff0000, v183
	v_lshlrev_b32_e32 v178, 16, v179
	v_and_b32_e32 v179, 0xffff0000, v179
	v_lshlrev_b32_e32 v174, 16, v175
	v_and_b32_e32 v175, 0xffff0000, v175
	v_lshlrev_b32_e32 v170, 16, v171
	v_and_b32_e32 v171, 0xffff0000, v171
	v_lshlrev_b32_e32 v166, 16, v167
	v_and_b32_e32 v167, 0xffff0000, v167
	v_lshlrev_b32_e32 v162, 16, v163
	v_and_b32_e32 v163, 0xffff0000, v163
	v_lshlrev_b32_e32 v158, 16, v159
	v_and_b32_e32 v159, 0xffff0000, v159
	v_lshlrev_b32_e32 v154, 16, v155
	v_and_b32_e32 v155, 0xffff0000, v155
	v_pk_mul_f32 v[40:41], v[40:41], v[142:143]
	v_lshlrev_b32_e32 v142, 16, v147
	v_and_b32_e32 v143, 0xffff0000, v147
	v_pk_mul_f32 v[16:17], v[16:17], v[134:135]
	v_pk_mul_f32 v[14:15], v[14:15], v[4:5]
	v_lshlrev_b32_e32 v4, 16, v138
	v_and_b32_e32 v5, 0xffff0000, v138
	v_lshlrev_b32_e32 v134, 16, v139
	v_and_b32_e32 v135, 0xffff0000, v139
	v_pk_mul_f32 v[128:129], v[128:129], v[214:215]
	v_lshlrev_b32_e32 v214, 16, v217
	v_and_b32_e32 v215, 0xffff0000, v217
	v_pk_mul_f32 v[124:125], v[124:125], v[190:191]
	v_lshlrev_b32_e32 v190, 16, v193
	v_and_b32_e32 v191, 0xffff0000, v193
	v_pk_mul_f32 v[116:117], v[116:117], v[186:187]
	v_lshlrev_b32_e32 v186, 16, v189
	v_and_b32_e32 v187, 0xffff0000, v189
	v_pk_mul_f32 v[108:109], v[108:109], v[182:183]
	v_lshlrev_b32_e32 v182, 16, v185
	v_and_b32_e32 v183, 0xffff0000, v185
	v_pk_mul_f32 v[100:101], v[100:101], v[178:179]
	v_lshlrev_b32_e32 v178, 16, v181
	v_and_b32_e32 v179, 0xffff0000, v181
	v_pk_mul_f32 v[92:93], v[92:93], v[174:175]
	v_lshlrev_b32_e32 v174, 16, v177
	v_and_b32_e32 v175, 0xffff0000, v177
	v_pk_mul_f32 v[84:85], v[84:85], v[170:171]
	v_lshlrev_b32_e32 v170, 16, v173
	v_and_b32_e32 v171, 0xffff0000, v173
	v_pk_mul_f32 v[76:77], v[76:77], v[166:167]
	v_lshlrev_b32_e32 v166, 16, v169
	v_and_b32_e32 v167, 0xffff0000, v169
	v_pk_mul_f32 v[68:69], v[68:69], v[162:163]
	v_lshlrev_b32_e32 v162, 16, v165
	v_and_b32_e32 v163, 0xffff0000, v165
	v_pk_mul_f32 v[60:61], v[60:61], v[158:159]
	v_lshlrev_b32_e32 v158, 16, v161
	v_and_b32_e32 v159, 0xffff0000, v161
	v_pk_mul_f32 v[52:53], v[52:53], v[154:155]
	v_lshlrev_b32_e32 v154, 16, v157
	v_and_b32_e32 v155, 0xffff0000, v157
	v_pk_mul_f32 v[36:37], v[36:37], v[142:143]
	v_lshlrev_b32_e32 v142, 16, v149
	v_and_b32_e32 v143, 0xffff0000, v149
	v_pk_mul_f32 v[12:13], v[12:13], v[134:135]
	v_pk_mul_f32 v[10:11], v[10:11], v[4:5]
	v_lshlrev_b32_e32 v4, 16, v140
	v_and_b32_e32 v5, 0xffff0000, v140
	v_lshlrev_b32_e32 v134, 16, v141
	v_and_b32_e32 v135, 0xffff0000, v141
	v_pk_mul_f32 v[132:133], v[132:133], v[214:215]
	v_pk_mul_f32 v[120:121], v[120:121], v[190:191]
	v_pk_mul_f32 v[112:113], v[112:113], v[186:187]
	v_pk_mul_f32 v[104:105], v[104:105], v[182:183]
	v_pk_mul_f32 v[96:97], v[96:97], v[178:179]
	v_pk_mul_f32 v[88:89], v[88:89], v[174:175]
	v_pk_mul_f32 v[80:81], v[80:81], v[170:171]
	v_pk_mul_f32 v[72:73], v[72:73], v[166:167]
	v_pk_mul_f32 v[64:65], v[64:65], v[162:163]
	v_pk_mul_f32 v[56:57], v[56:57], v[158:159]
	v_pk_mul_f32 v[48:49], v[48:49], v[154:155]
	v_pk_mul_f32 v[32:33], v[32:33], v[142:143]
	v_pk_mul_f32 v[8:9], v[8:9], v[134:135]
	v_pk_mul_f32 v[6:7], v[6:7], v[4:5]
	.p2align	6

; #define PG8_STAGE(bufoff, gbase, voff) do { _Pragma("unroll") for (int _i = 0; _i < 2; ++_i) \
;         __builtin_amdgcn_global_load_lds((const unsigned*)((const char*)(gbase) + (voff)[_i]), (PG8_LAS unsigned*)(lds + (bufoff) + ldsw + _i * 8192), 16, 0, 0); } while (0)
; #define PG8_LDA(dst, b, h) do { _Pragma("unroll") for (int m = 0; m < 4; ++m) _Pragma("unroll") for (int k = 0; k < 2; ++k) dst[m][k] = *(const PG8_LAS bf16x8*)(lds + PG8_SA(b, h) + aoff + m * 2048 + k * 1024); } while (0)
; #define PG8_LDB(dst, b, h) do { _Pragma("unroll") for (int n = 0; n < 2; ++n) _Pragma("unroll") for (int k = 0; k < 2; ++k) dst[n][k] = *(const PG8_LAS bf16x8*)(lds + PG8_SB(b, h) + boff + n * 2048 + k * 1024); } while (0)
; #define PG8_WAIT_V(n) asm volatile("s_waitcnt vmcnt(" #n ")" ::: "memory")
; #define PG8_WAIT_L(n) asm volatile("s_waitcnt lgkmcnt(" #n ")" ::: "memory")
; template <class Epi, class Sched, bool ALIGN_EPI = false, bool SP2 = false, bool ACHUNK = false>
; __device__ __forceinline__ void gemm_phase(PG8_LAS unsigned char* lds, const Gemm g, const Sched& S, const Epi& E) {
;     ...
;         const bool has_next = S.next(ui + 1, nxt);
;         const char* nA = has_next ? (const char*)g.A + (size_t)nxt.pm * tstepA : cA; const char* nB = has_next ? (const char*)g.Bt + (size_t)nxt.pn * tstepB : cB;
;         for (int t = 0; t < nt; t += 2) {
;             const bool last = (t == nt - 2);
;             if constexpr (Epi::HAS_MID) { if (t == Epi::MID_T) E.mid(acc, cur, wr, wc, fr, fq, ShflDev{}); }
;             const char* a1 = cA + (size_t)(t + 1) * kstep;
;             const char* a2 = last ? nA : cA + (size_t)(t + 2) * kstep; const char* b2 = last ? nB : cB + (size_t)(t + 2) * kstep;
;             const char* a3 = a2 + kstep; const char* b3 = b2 + kstep;
;             if (last && has_next) S.a_ready(nxt);
;             if constexpr (SP2) {
;             PG8_LDB(B0, 0, 0); PG8_LDB(B1, 0, 1); PG8_SCHED; PG8_LDA(At, 0, 0); PG8_STAGE(PG8_SA(1, 1), a1 + hstepA, voffA);
;             PG8_WAIT_V(8); PG8_WAIT_L(0); PG8_BAR; PG8_MMA(0, 0, At, B0); PG8_MMA(0, 1, At, B1); PG8_BAR; PG8_SCHED;
;             PG8_LDA(At, 0, 1); PG8_STAGE(PG8_SB(0, 0), b2, voffB); PG8_STAGE(PG8_SB(0, 1), b2 + hstepB, voffB); PG8_STAGE(PG8_SA(0, 0), a2, voffA);
;             PG8_WAIT_V(8); PG8_WAIT_L(0); PG8_BAR; PG8_MMA(1, 0, At, B0); PG8_MMA(1, 1, At, B1); PG8_BAR; PG8_SCHED;
.LBB0_351:
	s_andn2_b64 vcc, exec, s[4:5]
	s_cbranch_vccnz .LBB0_342
	s_add_u32 s40, s18, 0x100
	s_addc_u32 s41, s19, 0
	s_add_u32 s18, s20, 0x80
	s_addc_u32 s19, s21, 0
	s_mov_b32 s20, 0
	s_add_i32 s42, s20, 2
	s_add_u32 s43, s18, 0x80
	s_addc_u32 s21, s19, 0
	s_add_i32 s46, 0, 0x10000
	s_cmp_eq_u32 s33, s20
	s_cselect_b32 s21, s13, s21
	s_cselect_b32 s20, s12, s43
	v_add_u32_e32 v153, s46, v143
	s_cselect_b32 s45, s17, s41
	s_cselect_b32 s44, s16, s40
	s_add_i32 s43, 0, 0x14000
	ds_read_b128 v[154:157], v153
	ds_read_b128 v[158:161], v153 offset:1024
	ds_read_b128 v[162:165], v153 offset:2048
	ds_read_b128 v[166:169], v153 offset:3072
	v_add_u32_e32 v153, s43, v143
	ds_read_b128 v[170:173], v153
	ds_read_b128 v[174:177], v153 offset:1024
	ds_read_b128 v[178:181], v153 offset:2048
	ds_read_b128 v[182:185], v153 offset:3072
	s_add_i32 m0, s25, 0xc000
	ds_read_b128 v[186:189], v152
	ds_read_b128 v[190:193], v152 offset:1024
	ds_read_b128 v[198:201], v152 offset:2048
	ds_read_b128 v[202:205], v152 offset:3072
	ds_read_b128 v[206:209], v152 offset:4096
	ds_read_b128 v[210:213], v152 offset:5120
	ds_read_b128 v[214:217], v152 offset:6144
	ds_read_b128 v[218:221], v152 offset:7168
	global_load_lds_dwordx4 v138, s[18:19]
	s_add_i32 m0, s25, 0xe000
	s_nop 0
	global_load_lds_dwordx4 v140, s[18:19]
	s_waitcnt vmcnt(8)
	s_waitcnt lgkmcnt(0)
	s_barrier
	s_setprio 1
	v_mfma_f32_16x16x32_bf16 v[124:127], v[154:157], v[186:189], 0
	v_mfma_f32_16x16x32_bf16 v[128:131], v[162:165], v[186:189], 0
	v_mfma_f32_16x16x32_bf16 v[112:115], v[154:157], v[198:201], 0
	v_mfma_f32_16x16x32_bf16 v[108:111], v[162:165], v[198:201], 0
	v_mfma_f32_16x16x32_bf16 v[96:99], v[154:157], v[206:209], 0
	v_mfma_f32_16x16x32_bf16 v[92:95], v[162:165], v[206:209], 0
	v_mfma_f32_16x16x32_bf16 v[80:83], v[154:157], v[214:217], 0
	v_mfma_f32_16x16x32_bf16 v[76:79], v[162:165], v[214:217], 0
	v_mfma_f32_16x16x32_bf16 v[124:127], v[158:161], v[190:193], v[124:127]
	v_mfma_f32_16x16x32_bf16 v[128:131], v[166:169], v[190:193], v[128:131]
	v_mfma_f32_16x16x32_bf16 v[112:115], v[158:161], v[202:205], v[112:115]
	v_mfma_f32_16x16x32_bf16 v[108:111], v[166:169], v[202:205], v[108:111]
	v_mfma_f32_16x16x32_bf16 v[96:99], v[158:161], v[210:213], v[96:99]
	v_mfma_f32_16x16x32_bf16 v[92:95], v[166:169], v[210:213], v[92:95]
	v_mfma_f32_16x16x32_bf16 v[80:83], v[158:161], v[218:221], v[80:83]
	v_mfma_f32_16x16x32_bf16 v[76:79], v[166:169], v[218:221], v[76:79]
	s_setprio 0
	s_setprio 1
	v_mfma_f32_16x16x32_bf16 v[120:123], v[170:173], v[186:189], 0
	v_mfma_f32_16x16x32_bf16 v[116:119], v[178:181], v[186:189], 0
	v_mfma_f32_16x16x32_bf16 v[104:107], v[170:173], v[198:201], 0
	v_mfma_f32_16x16x32_bf16 v[100:103], v[178:181], v[198:201], 0
	v_mfma_f32_16x16x32_bf16 v[88:91], v[170:173], v[206:209], 0
	v_mfma_f32_16x16x32_bf16 v[84:87], v[178:181], v[206:209], 0
	v_mfma_f32_16x16x32_bf16 v[72:75], v[170:173], v[214:217], 0
	v_mfma_f32_16x16x32_bf16 v[68:71], v[178:181], v[214:217], 0
	v_mfma_f32_16x16x32_bf16 v[120:123], v[174:177], v[190:193], v[120:123]
	v_mfma_f32_16x16x32_bf16 v[116:119], v[182:185], v[190:193], v[116:119]
	v_mfma_f32_16x16x32_bf16 v[104:107], v[174:177], v[202:205], v[104:107]
	v_mfma_f32_16x16x32_bf16 v[100:103], v[182:185], v[202:205], v[100:103]
	v_mfma_f32_16x16x32_bf16 v[88:91], v[174:177], v[210:213], v[88:91]
	v_mfma_f32_16x16x32_bf16 v[84:87], v[182:185], v[210:213], v[84:87]
	v_mfma_f32_16x16x32_bf16 v[72:75], v[174:177], v[218:221], v[72:75]
	v_mfma_f32_16x16x32_bf16 v[68:71], v[182:185], v[218:221], v[68:71]
	s_setprio 0
	s_barrier
	s_add_i32 s46, s46, s24
	s_mov_b32 m0, s46
	ds_read_b128 v[186:189], v152 offset:16384
	ds_read_b128 v[190:193], v152 offset:17408
	ds_read_b128 v[198:201], v152 offset:18432
	ds_read_b128 v[202:205], v152 offset:19456
	ds_read_b128 v[206:209], v152 offset:20480
	ds_read_b128 v[210:213], v152 offset:21504
	ds_read_b128 v[214:217], v152 offset:22528
	ds_read_b128 v[218:221], v152 offset:23552
	global_load_lds_dwordx4 v2, s[44:45]
	s_add_i32 m0, s46, 0x2000
	s_add_i32 s43, s43, s24
	global_load_lds_dwordx4 v136, s[44:45]
	s_add_u32 s44, s44, s0
	s_addc_u32 s45, s45, s1
	s_mov_b64 vcc, s[44:45]
	s_sub_u32 s98, s44, s0
	s_subb_u32 s99, s45, s1
	s_mov_b32 m0, s43
	s_nop 0
	global_load_lds_dwordx4 v2, s[44:45]
	s_add_i32 m0, s43, 0x2000
	s_nop 0
	global_load_lds_dwordx4 v136, s[44:45]
	s_mov_b32 m0, s25
	s_nop 0
	global_load_lds_dwordx4 v132, s[20:21]
	s_mov_b32 m0, s26
	s_nop 0
	global_load_lds_dwordx4 v134, s[20:21]
	s_waitcnt vmcnt(8)
	s_waitcnt lgkmcnt(0)
	s_barrier
	s_setprio 1
	v_mfma_f32_16x16x32_bf16 v[64:67], v[154:157], v[186:189], 0
	v_mfma_f32_16x16x32_bf16 v[60:63], v[162:165], v[186:189], 0
	v_mfma_f32_16x16x32_bf16 v[48:51], v[154:157], v[198:201], 0
	v_mfma_f32_16x16x32_bf16 v[44:47], v[162:165], v[198:201], 0
	v_mfma_f32_16x16x32_bf16 v[32:35], v[154:157], v[206:209], 0
	v_mfma_f32_16x16x32_bf16 v[28:31], v[162:165], v[206:209], 0
	v_mfma_f32_16x16x32_bf16 v[16:19], v[154:157], v[214:217], 0
	v_mfma_f32_16x16x32_bf16 v[12:15], v[162:165], v[214:217], 0
	v_mfma_f32_16x16x32_bf16 v[64:67], v[158:161], v[190:193], v[64:67]
	v_mfma_f32_16x16x32_bf16 v[60:63], v[166:169], v[190:193], v[60:63]
	v_mfma_f32_16x16x32_bf16 v[48:51], v[158:161], v[202:205], v[48:51]
	v_mfma_f32_16x16x32_bf16 v[44:47], v[166:169], v[202:205], v[44:47]
	v_mfma_f32_16x16x32_bf16 v[32:35], v[158:161], v[210:213], v[32:35]
	v_mfma_f32_16x16x32_bf16 v[28:31], v[166:169], v[210:213], v[28:31]
	v_mfma_f32_16x16x32_bf16 v[16:19], v[158:161], v[218:221], v[16:19]
	v_mfma_f32_16x16x32_bf16 v[12:15], v[166:169], v[218:221], v[12:15]
	s_setprio 0
	s_setprio 1
	v_mfma_f32_16x16x32_bf16 v[56:59], v[170:173], v[186:189], 0
	v_mfma_f32_16x16x32_bf16 v[52:55], v[178:181], v[186:189], 0
	v_mfma_f32_16x16x32_bf16 v[40:43], v[170:173], v[198:201], 0
	v_mfma_f32_16x16x32_bf16 v[36:39], v[178:181], v[198:201], 0
	v_mfma_f32_16x16x32_bf16 v[24:27], v[170:173], v[206:209], 0
	v_mfma_f32_16x16x32_bf16 v[20:23], v[178:181], v[206:209], 0
	v_mfma_f32_16x16x32_bf16 v[8:11], v[170:173], v[214:217], 0
	v_mfma_f32_16x16x32_bf16 v[4:7], v[178:181], v[214:217], 0
	v_mfma_f32_16x16x32_bf16 v[56:59], v[174:177], v[190:193], v[56:59]
	v_mfma_f32_16x16x32_bf16 v[52:55], v[182:185], v[190:193], v[52:55]
	v_mfma_f32_16x16x32_bf16 v[40:43], v[174:177], v[202:205], v[40:43]
	v_mfma_f32_16x16x32_bf16 v[36:39], v[182:185], v[202:205], v[36:39]
	v_mfma_f32_16x16x32_bf16 v[24:27], v[174:177], v[210:213], v[24:27]
	v_mfma_f32_16x16x32_bf16 v[20:23], v[182:185], v[210:213], v[20:23]
	v_mfma_f32_16x16x32_bf16 v[8:11], v[174:177], v[218:221], v[8:11]
	v_mfma_f32_16x16x32_bf16 v[4:7], v[182:185], v[218:221], v[4:7]
	s_setprio 0
	s_barrier
	s_branch .Lpe_join_353
	.p2align	6

; #define PG8_STAGE(bufoff, gbase, voff) do { _Pragma("unroll") for (int _i = 0; _i < 2; ++_i) \
;         __builtin_amdgcn_global_load_lds((const unsigned*)((const char*)(gbase) + (voff)[_i]), (PG8_LAS unsigned*)(lds + (bufoff) + ldsw + _i * 8192), 16, 0, 0); } while (0)
; #define PG8_LDA(dst, b, h) do { _Pragma("unroll") for (int m = 0; m < 4; ++m) _Pragma("unroll") for (int k = 0; k < 2; ++k) dst[m][k] = *(const PG8_LAS bf16x8*)(lds + PG8_SA(b, h) + aoff + m * 2048 + k * 1024); } while (0)
; #define PG8_LDB(dst, b, h) do { _Pragma("unroll") for (int n = 0; n < 2; ++n) _Pragma("unroll") for (int k = 0; k < 2; ++k) dst[n][k] = *(const PG8_LAS bf16x8*)(lds + PG8_SB(b, h) + boff + n * 2048 + k * 1024); } while (0)
; #define PG8_MMA(ai, bj, At, Bt) do { __builtin_amdgcn_s_setprio(1); _Pragma("unroll") for (int m = 0; m < 4; ++m) _Pragma("unroll") for (int n = 0; n < 2; ++n) _Pragma("unroll") for (int k = 0; k < 2; ++k) \
;         acc[ai][bj][m][n] = __builtin_amdgcn_mfma_f32_16x16x32_bf16(Bt[n][k], At[m][k], acc[ai][bj][m][n], 0, 0, 0); __builtin_amdgcn_s_setprio(0); } while (0)
; #define PG8_WAIT_V(n) asm volatile("s_waitcnt vmcnt(" #n ")" ::: "memory")
; #define PG8_WAIT_L(n) asm volatile("s_waitcnt lgkmcnt(" #n ")" ::: "memory")
; #define PG8_BAR __builtin_amdgcn_s_barrier()
; template <class Epi, class Sched, bool ALIGN_EPI = false, bool SP2 = false, bool ACHUNK = false>
; __device__ __forceinline__ void gemm_phase(PG8_LAS unsigned char* lds, const Gemm g, const Sched& S, const Epi& E) {
;     ...
;             const char* a1 = cA + (size_t)(t + 1) * kstep;
;             const char* a2 = last ? nA : cA + (size_t)(t + 2) * kstep; const char* b2 = last ? nB : cB + (size_t)(t + 2) * kstep;
;             const char* a3 = a2 + kstep; const char* b3 = b2 + kstep;
;             if (last && has_next) S.a_ready(nxt);
;             if constexpr (SP2) {
;             PG8_LDB(B0, 0, 0); PG8_LDB(B1, 0, 1); PG8_SCHED; PG8_LDA(At, 0, 0); PG8_STAGE(PG8_SA(1, 1), a1 + hstepA, voffA);
;             PG8_WAIT_V(8); PG8_WAIT_L(0); PG8_BAR; PG8_MMA(0, 0, At, B0); PG8_MMA(0, 1, At, B1); PG8_BAR; PG8_SCHED;
;             PG8_LDA(At, 0, 1); PG8_STAGE(PG8_SB(0, 0), b2, voffB); PG8_STAGE(PG8_SB(0, 1), b2 + hstepB, voffB); PG8_STAGE(PG8_SA(0, 0), a2, voffA);
;             PG8_WAIT_V(8); PG8_WAIT_L(0); PG8_BAR; PG8_MMA(1, 0, At, B0); PG8_MMA(1, 1, At, B1); PG8_BAR; PG8_SCHED;
.LBB0_375:
	s_andn2_b64 vcc, exec, s[34:35]
	s_cbranch_vccnz .LBB0_379
	s_add_u32 s4, s4, 0x80
	s_addc_u32 s5, s5, 0
	s_add_u32 s8, s6, 0x100
	s_addc_u32 s9, s7, 0
	s_mov_b32 s6, 0
	s_add_i32 s48, s6, 2
	s_add_u32 s49, s4, 0x80
	s_addc_u32 s7, s5, 0
	s_add_i32 s52, 0, 0x10000
	s_cmp_eq_u32 s27, s6
	s_cselect_b32 s7, s1, s7
	s_cselect_b32 s6, s0, s49
	v_add_u32_e32 v2, s52, v175
	s_cselect_b32 s51, s43, s9
	s_cselect_b32 s50, s42, s8
	s_add_i32 s49, 0, 0x14000
	s_waitcnt lgkmcnt(0)
	ds_read_b128 v[146:149], v2
	ds_read_b128 v[150:153], v2 offset:1024
	ds_read_b128 v[154:157], v2 offset:2048
	ds_read_b128 v[158:161], v2 offset:3072
	v_add_u32_e32 v2, s49, v175
	ds_read_b128 v[162:165], v2
	ds_read_b128 v[166:169], v2 offset:1024
	ds_read_b128 v[170:173], v2 offset:2048
	ds_read_b128 v[180:183], v2 offset:3072
	s_add_i32 m0, s20, 0xc000
	ds_read_b128 v[184:187], v179
	ds_read_b128 v[188:191], v179 offset:1024
	ds_read_b128 v[198:201], v179 offset:2048
	ds_read_b128 v[202:205], v179 offset:3072
	ds_read_b128 v[206:209], v179 offset:4096
	ds_read_b128 v[210:213], v179 offset:5120
	ds_read_b128 v[214:217], v179 offset:6144
	ds_read_b128 v[218:221], v179 offset:7168
	global_load_lds_dwordx4 v142, s[4:5]
	s_add_i32 m0, s20, 0xe000
	s_nop 0
	global_load_lds_dwordx4 v144, s[4:5]
	s_waitcnt vmcnt(8)
	s_waitcnt lgkmcnt(0)
	s_barrier
	s_setprio 1
	v_mfma_f32_16x16x32_bf16 v[124:127], v[146:149], v[184:187], 0
	v_mfma_f32_16x16x32_bf16 v[116:119], v[154:157], v[184:187], 0
	v_mfma_f32_16x16x32_bf16 v[108:111], v[146:149], v[198:201], 0
	v_mfma_f32_16x16x32_bf16 v[100:103], v[154:157], v[198:201], 0
	v_mfma_f32_16x16x32_bf16 v[92:95], v[146:149], v[206:209], 0
	v_mfma_f32_16x16x32_bf16 v[84:87], v[154:157], v[206:209], 0
	v_mfma_f32_16x16x32_bf16 v[76:79], v[146:149], v[214:217], 0
	v_mfma_f32_16x16x32_bf16 v[68:71], v[154:157], v[214:217], 0
	v_mfma_f32_16x16x32_bf16 v[124:127], v[150:153], v[188:191], v[124:127]
	v_mfma_f32_16x16x32_bf16 v[116:119], v[158:161], v[188:191], v[116:119]
	v_mfma_f32_16x16x32_bf16 v[108:111], v[150:153], v[202:205], v[108:111]
	v_mfma_f32_16x16x32_bf16 v[100:103], v[158:161], v[202:205], v[100:103]
	v_mfma_f32_16x16x32_bf16 v[92:95], v[150:153], v[210:213], v[92:95]
	v_mfma_f32_16x16x32_bf16 v[84:87], v[158:161], v[210:213], v[84:87]
	v_mfma_f32_16x16x32_bf16 v[76:79], v[150:153], v[218:221], v[76:79]
	v_mfma_f32_16x16x32_bf16 v[68:71], v[158:161], v[218:221], v[68:71]
	s_setprio 0
	s_setprio 1
	v_mfma_f32_16x16x32_bf16 v[128:131], v[162:165], v[184:187], 0
	v_mfma_f32_16x16x32_bf16 v[120:123], v[170:173], v[184:187], 0
	v_mfma_f32_16x16x32_bf16 v[112:115], v[162:165], v[198:201], 0
	v_mfma_f32_16x16x32_bf16 v[104:107], v[170:173], v[198:201], 0
	v_mfma_f32_16x16x32_bf16 v[96:99], v[162:165], v[206:209], 0
	v_mfma_f32_16x16x32_bf16 v[88:91], v[170:173], v[206:209], 0
	v_mfma_f32_16x16x32_bf16 v[80:83], v[162:165], v[214:217], 0
	v_mfma_f32_16x16x32_bf16 v[72:75], v[170:173], v[214:217], 0
	v_mfma_f32_16x16x32_bf16 v[128:131], v[166:169], v[188:191], v[128:131]
	v_mfma_f32_16x16x32_bf16 v[120:123], v[180:183], v[188:191], v[120:123]
	v_mfma_f32_16x16x32_bf16 v[112:115], v[166:169], v[202:205], v[112:115]
	v_mfma_f32_16x16x32_bf16 v[104:107], v[180:183], v[202:205], v[104:107]
	v_mfma_f32_16x16x32_bf16 v[96:99], v[166:169], v[210:213], v[96:99]
	v_mfma_f32_16x16x32_bf16 v[88:91], v[180:183], v[210:213], v[88:91]
	v_mfma_f32_16x16x32_bf16 v[80:83], v[166:169], v[218:221], v[80:83]
	v_mfma_f32_16x16x32_bf16 v[72:75], v[180:183], v[218:221], v[72:75]
	s_setprio 0
	s_barrier
	s_add_i32 s52, s52, s13
	s_mov_b32 m0, s52
	ds_read_b128 v[184:187], v179 offset:16384
	ds_read_b128 v[188:191], v179 offset:17408
	ds_read_b128 v[198:201], v179 offset:18432
	ds_read_b128 v[202:205], v179 offset:19456
	ds_read_b128 v[206:209], v179 offset:20480
	ds_read_b128 v[210:213], v179 offset:21504
	ds_read_b128 v[214:217], v179 offset:22528
	ds_read_b128 v[218:221], v179 offset:23552
	global_load_lds_dwordx4 v134, s[50:51]
	s_add_i32 m0, s52, 0x2000
	s_add_i32 s49, s49, s13
	global_load_lds_dwordx4 v138, s[50:51]
	s_add_u32 s50, s50, s18
	s_addc_u32 s51, s51, s19
	s_mov_b64 vcc, s[50:51]
	s_sub_u32 s98, s50, s18
	s_subb_u32 s99, s51, s19
	s_mov_b32 m0, s49
	s_nop 0
	global_load_lds_dwordx4 v134, s[50:51]
	s_add_i32 m0, s49, 0x2000
	s_nop 0
	global_load_lds_dwordx4 v138, s[50:51]
	s_mov_b32 m0, s20
	s_nop 0
	global_load_lds_dwordx4 v132, s[6:7]
	s_mov_b32 m0, s21
	s_nop 0
	global_load_lds_dwordx4 v136, s[6:7]
	s_waitcnt vmcnt(8)
	s_waitcnt lgkmcnt(0)
	s_barrier
	s_setprio 1
	v_mfma_f32_16x16x32_bf16 v[60:63], v[146:149], v[184:187], 0
	v_mfma_f32_16x16x32_bf16 v[52:55], v[154:157], v[184:187], 0
	v_mfma_f32_16x16x32_bf16 v[44:47], v[146:149], v[198:201], 0
	v_mfma_f32_16x16x32_bf16 v[36:39], v[154:157], v[198:201], 0
	v_mfma_f32_16x16x32_bf16 v[28:31], v[146:149], v[206:209], 0
	v_mfma_f32_16x16x32_bf16 v[20:23], v[154:157], v[206:209], 0
	v_mfma_f32_16x16x32_bf16 v[12:15], v[146:149], v[214:217], 0
	v_mfma_f32_16x16x32_bf16 v[4:7], v[154:157], v[214:217], 0
	v_mfma_f32_16x16x32_bf16 v[60:63], v[150:153], v[188:191], v[60:63]
	v_mfma_f32_16x16x32_bf16 v[52:55], v[158:161], v[188:191], v[52:55]
	v_mfma_f32_16x16x32_bf16 v[44:47], v[150:153], v[202:205], v[44:47]
	v_mfma_f32_16x16x32_bf16 v[36:39], v[158:161], v[202:205], v[36:39]
	v_mfma_f32_16x16x32_bf16 v[28:31], v[150:153], v[210:213], v[28:31]
	v_mfma_f32_16x16x32_bf16 v[20:23], v[158:161], v[210:213], v[20:23]
	v_mfma_f32_16x16x32_bf16 v[12:15], v[150:153], v[218:221], v[12:15]
	v_mfma_f32_16x16x32_bf16 v[4:7], v[158:161], v[218:221], v[4:7]
	s_setprio 0
	s_setprio 1
	v_mfma_f32_16x16x32_bf16 v[64:67], v[162:165], v[184:187], 0
	v_mfma_f32_16x16x32_bf16 v[56:59], v[170:173], v[184:187], 0
	v_mfma_f32_16x16x32_bf16 v[48:51], v[162:165], v[198:201], 0
	v_mfma_f32_16x16x32_bf16 v[40:43], v[170:173], v[198:201], 0
	v_mfma_f32_16x16x32_bf16 v[32:35], v[162:165], v[206:209], 0
	v_mfma_f32_16x16x32_bf16 v[24:27], v[170:173], v[206:209], 0
	v_mfma_f32_16x16x32_bf16 v[16:19], v[162:165], v[214:217], 0
	v_mfma_f32_16x16x32_bf16 v[8:11], v[170:173], v[214:217], 0
	v_mfma_f32_16x16x32_bf16 v[64:67], v[166:169], v[188:191], v[64:67]
	v_mfma_f32_16x16x32_bf16 v[56:59], v[180:183], v[188:191], v[56:59]
	v_mfma_f32_16x16x32_bf16 v[48:51], v[166:169], v[202:205], v[48:51]
	v_mfma_f32_16x16x32_bf16 v[40:43], v[180:183], v[202:205], v[40:43]
	v_mfma_f32_16x16x32_bf16 v[32:35], v[166:169], v[210:213], v[32:35]
	v_mfma_f32_16x16x32_bf16 v[24:27], v[180:183], v[210:213], v[24:27]
	v_mfma_f32_16x16x32_bf16 v[16:19], v[166:169], v[218:221], v[16:19]
	v_mfma_f32_16x16x32_bf16 v[8:11], v[180:183], v[218:221], v[8:11]
	s_setprio 0
	s_barrier
	s_branch .Lpe_join_377
	.p2align	6

; #define PG8_STAGE(bufoff, gbase, voff) do { _Pragma("unroll") for (int _i = 0; _i < 2; ++_i) \
;         __builtin_amdgcn_global_load_lds((const unsigned*)((const char*)(gbase) + (voff)[_i]), (PG8_LAS unsigned*)(lds + (bufoff) + ldsw + _i * 8192), 16, 0, 0); } while (0)
; #define PG8_LDA(dst, b, h) do { _Pragma("unroll") for (int m = 0; m < 4; ++m) _Pragma("unroll") for (int k = 0; k < 2; ++k) dst[m][k] = *(const PG8_LAS bf16x8*)(lds + PG8_SA(b, h) + aoff + m * 2048 + k * 1024); } while (0)
; #define PG8_LDB(dst, b, h) do { _Pragma("unroll") for (int n = 0; n < 2; ++n) _Pragma("unroll") for (int k = 0; k < 2; ++k) dst[n][k] = *(const PG8_LAS bf16x8*)(lds + PG8_SB(b, h) + boff + n * 2048 + k * 1024); } while (0)
; #define PG8_MMA(ai, bj, At, Bt) do { __builtin_amdgcn_s_setprio(1); _Pragma("unroll") for (int m = 0; m < 4; ++m) _Pragma("unroll") for (int n = 0; n < 2; ++n) _Pragma("unroll") for (int k = 0; k < 2; ++k) \
;         acc[ai][bj][m][n] = __builtin_amdgcn_mfma_f32_16x16x32_bf16(Bt[n][k], At[m][k], acc[ai][bj][m][n], 0, 0, 0); __builtin_amdgcn_s_setprio(0); } while (0)
; #define PG8_WAIT_V(n) asm volatile("s_waitcnt vmcnt(" #n ")" ::: "memory")
; #define PG8_WAIT_L(n) asm volatile("s_waitcnt lgkmcnt(" #n ")" ::: "memory")
; #define PG8_BAR __builtin_amdgcn_s_barrier()
; template <class Epi, class Sched, bool ALIGN_EPI = false, bool SP2 = false, bool ACHUNK = false>
; __device__ __forceinline__ void gemm_phase(PG8_LAS unsigned char* lds, const Gemm g, const Sched& S, const Epi& E) {
;     ...
;             const char* a1 = cA + (size_t)(t + 1) * kstep;
;             const char* a2 = last ? nA : cA + (size_t)(t + 2) * kstep; const char* b2 = last ? nB : cB + (size_t)(t + 2) * kstep;
;             const char* a3 = a2 + kstep; const char* b3 = b2 + kstep;
;             if (last && has_next) S.a_ready(nxt);
;             if constexpr (SP2) {
;             PG8_LDB(B0, 0, 0); PG8_LDB(B1, 0, 1); PG8_SCHED; PG8_LDA(At, 0, 0); PG8_STAGE(PG8_SA(1, 1), a1 + hstepA, voffA);
;             PG8_WAIT_V(8); PG8_WAIT_L(0); PG8_BAR; PG8_MMA(0, 0, At, B0); PG8_MMA(0, 1, At, B1); PG8_BAR; PG8_SCHED;
;             PG8_LDA(At, 0, 1); PG8_STAGE(PG8_SB(0, 0), b2, voffB); PG8_STAGE(PG8_SB(0, 1), b2 + hstepB, voffB); PG8_STAGE(PG8_SA(0, 0), a2, voffA);
;             PG8_WAIT_V(8); PG8_WAIT_L(0); PG8_BAR; PG8_MMA(1, 0, At, B0); PG8_MMA(1, 1, At, B1); PG8_BAR; PG8_SCHED;
.Lnl_pl_pe:
	s_add_i32 s9, 0, 0x14000
	v_add_u32_e32 v144, s15, v221
	v_add_u32_e32 v160, s9, v221
	ds_read_b128 v[132:135], v144
	ds_read_b128 v[136:139], v144 offset:1024
	ds_read_b128 v[140:143], v144 offset:2048
	ds_read_b128 v[144:147], v144 offset:3072
	ds_read_b128 v[148:151], v160
	ds_read_b128 v[152:155], v160 offset:1024
	ds_read_b128 v[156:159], v160 offset:2048
	ds_read_b128 v[160:163], v160 offset:3072
	s_add_i32 m0, s27, 0xc000
	ds_read_b128 v[178:181], v223
	ds_read_b128 v[182:185], v223 offset:1024
	ds_read_b128 v[186:189], v223 offset:2048
	ds_read_b128 v[190:193], v223 offset:3072
	ds_read_b128 v[198:201], v223 offset:4096
	ds_read_b128 v[202:205], v223 offset:5120
	ds_read_b128 v[206:209], v223 offset:6144
	ds_read_b128 v[210:213], v223 offset:7168
	global_load_lds_dwordx4 v174, s[0:1]
	s_add_i32 m0, s27, 0xe000
	s_nop 0
	global_load_lds_dwordx4 v176, s[0:1]
	s_waitcnt vmcnt(8)
	s_waitcnt lgkmcnt(0)
	s_barrier
	s_setprio 1
	v_mfma_f32_16x16x32_bf16 v[128:131], v[132:135], v[178:181], 0
	v_mfma_f32_16x16x32_bf16 v[124:127], v[140:143], v[178:181], 0
	v_mfma_f32_16x16x32_bf16 v[112:115], v[132:135], v[186:189], 0
	v_mfma_f32_16x16x32_bf16 v[108:111], v[140:143], v[186:189], 0
	v_mfma_f32_16x16x32_bf16 v[96:99], v[132:135], v[198:201], 0
	v_mfma_f32_16x16x32_bf16 v[92:95], v[140:143], v[198:201], 0
	v_mfma_f32_16x16x32_bf16 v[80:83], v[132:135], v[206:209], 0
	v_mfma_f32_16x16x32_bf16 v[76:79], v[140:143], v[206:209], 0
	v_mfma_f32_16x16x32_bf16 v[128:131], v[136:139], v[182:185], v[128:131]
	v_mfma_f32_16x16x32_bf16 v[124:127], v[144:147], v[182:185], v[124:127]
	v_mfma_f32_16x16x32_bf16 v[112:115], v[136:139], v[190:193], v[112:115]
	v_mfma_f32_16x16x32_bf16 v[108:111], v[144:147], v[190:193], v[108:111]
	v_mfma_f32_16x16x32_bf16 v[96:99], v[136:139], v[202:205], v[96:99]
	v_mfma_f32_16x16x32_bf16 v[92:95], v[144:147], v[202:205], v[92:95]
	v_mfma_f32_16x16x32_bf16 v[80:83], v[136:139], v[210:213], v[80:83]
	v_mfma_f32_16x16x32_bf16 v[76:79], v[144:147], v[210:213], v[76:79]
	s_setprio 0
	s_setprio 1
	v_mfma_f32_16x16x32_bf16 v[120:123], v[148:151], v[178:181], 0
	v_mfma_f32_16x16x32_bf16 v[116:119], v[156:159], v[178:181], 0
	v_mfma_f32_16x16x32_bf16 v[104:107], v[148:151], v[186:189], 0
	v_mfma_f32_16x16x32_bf16 v[100:103], v[156:159], v[186:189], 0
	v_mfma_f32_16x16x32_bf16 v[88:91], v[148:151], v[198:201], 0
	v_mfma_f32_16x16x32_bf16 v[84:87], v[156:159], v[198:201], 0
	v_mfma_f32_16x16x32_bf16 v[72:75], v[148:151], v[206:209], 0
	v_mfma_f32_16x16x32_bf16 v[68:71], v[156:159], v[206:209], 0
	v_mfma_f32_16x16x32_bf16 v[120:123], v[152:155], v[182:185], v[120:123]
	v_mfma_f32_16x16x32_bf16 v[116:119], v[160:163], v[182:185], v[116:119]
	v_mfma_f32_16x16x32_bf16 v[104:107], v[152:155], v[190:193], v[104:107]
	v_mfma_f32_16x16x32_bf16 v[100:103], v[160:163], v[190:193], v[100:103]
	v_mfma_f32_16x16x32_bf16 v[88:91], v[152:155], v[202:205], v[88:91]
	v_mfma_f32_16x16x32_bf16 v[84:87], v[160:163], v[202:205], v[84:87]
	v_mfma_f32_16x16x32_bf16 v[72:75], v[152:155], v[210:213], v[72:75]
	v_mfma_f32_16x16x32_bf16 v[68:71], v[160:163], v[210:213], v[68:71]
	s_setprio 0
	s_barrier
	s_add_i32 s15, s15, s26
	s_mov_b32 m0, s15
	ds_read_b128 v[178:181], v223 offset:16384
	ds_read_b128 v[182:185], v223 offset:17408
	ds_read_b128 v[186:189], v223 offset:18432
	ds_read_b128 v[190:193], v223 offset:19456
	ds_read_b128 v[198:201], v223 offset:20480
	ds_read_b128 v[202:205], v223 offset:21504
	ds_read_b128 v[206:209], v223 offset:22528
	ds_read_b128 v[210:213], v223 offset:23552
	global_load_lds_dwordx4 v2, s[16:17]
	s_add_i32 m0, s15, 0x2000
	s_add_i32 s9, s9, s26
	global_load_lds_dwordx4 v168, s[16:17]
	s_add_u32 s16, s16, s18
	s_addc_u32 s17, s17, s19
	s_mov_b64 vcc, s[16:17]
	s_sub_u32 s98, s16, s18
	s_subb_u32 s99, s17, s19
	s_mov_b32 m0, s9
	s_nop 0
	global_load_lds_dwordx4 v2, s[16:17]
	s_add_i32 m0, s9, 0x2000
	s_nop 0
	global_load_lds_dwordx4 v168, s[16:17]
	s_mov_b32 m0, s27
	s_nop 0
	global_load_lds_dwordx4 v164, s[4:5]
	s_mov_b32 m0, s36
	s_nop 0
	global_load_lds_dwordx4 v166, s[4:5]
	s_waitcnt vmcnt(8)
	s_waitcnt lgkmcnt(0)
	s_barrier
	s_setprio 1
	v_mfma_f32_16x16x32_bf16 v[64:67], v[132:135], v[178:181], 0
	v_mfma_f32_16x16x32_bf16 v[60:63], v[140:143], v[178:181], 0
	v_mfma_f32_16x16x32_bf16 v[48:51], v[132:135], v[186:189], 0
	v_mfma_f32_16x16x32_bf16 v[44:47], v[140:143], v[186:189], 0
	v_mfma_f32_16x16x32_bf16 v[32:35], v[132:135], v[198:201], 0
	v_mfma_f32_16x16x32_bf16 v[28:31], v[140:143], v[198:201], 0
	v_mfma_f32_16x16x32_bf16 v[16:19], v[132:135], v[206:209], 0
	v_mfma_f32_16x16x32_bf16 v[12:15], v[140:143], v[206:209], 0
	v_mfma_f32_16x16x32_bf16 v[64:67], v[136:139], v[182:185], v[64:67]
	v_mfma_f32_16x16x32_bf16 v[60:63], v[144:147], v[182:185], v[60:63]
	v_mfma_f32_16x16x32_bf16 v[48:51], v[136:139], v[190:193], v[48:51]
	v_mfma_f32_16x16x32_bf16 v[44:47], v[144:147], v[190:193], v[44:47]
	v_mfma_f32_16x16x32_bf16 v[32:35], v[136:139], v[202:205], v[32:35]
	v_mfma_f32_16x16x32_bf16 v[28:31], v[144:147], v[202:205], v[28:31]
	v_mfma_f32_16x16x32_bf16 v[16:19], v[136:139], v[210:213], v[16:19]
	v_mfma_f32_16x16x32_bf16 v[12:15], v[144:147], v[210:213], v[12:15]
	s_setprio 0
	s_setprio 1
	v_mfma_f32_16x16x32_bf16 v[56:59], v[148:151], v[178:181], 0
	v_mfma_f32_16x16x32_bf16 v[52:55], v[156:159], v[178:181], 0
	v_mfma_f32_16x16x32_bf16 v[40:43], v[148:151], v[186:189], 0
	v_mfma_f32_16x16x32_bf16 v[36:39], v[156:159], v[186:189], 0
	v_mfma_f32_16x16x32_bf16 v[24:27], v[148:151], v[198:201], 0
	v_mfma_f32_16x16x32_bf16 v[20:23], v[156:159], v[198:201], 0
	v_mfma_f32_16x16x32_bf16 v[8:11], v[148:151], v[206:209], 0
	v_mfma_f32_16x16x32_bf16 v[4:7], v[156:159], v[206:209], 0
	v_mfma_f32_16x16x32_bf16 v[56:59], v[152:155], v[182:185], v[56:59]
	v_mfma_f32_16x16x32_bf16 v[52:55], v[160:163], v[182:185], v[52:55]
	v_mfma_f32_16x16x32_bf16 v[40:43], v[152:155], v[190:193], v[40:43]
	v_mfma_f32_16x16x32_bf16 v[36:39], v[160:163], v[190:193], v[36:39]
	v_mfma_f32_16x16x32_bf16 v[24:27], v[152:155], v[202:205], v[24:27]
	v_mfma_f32_16x16x32_bf16 v[20:23], v[160:163], v[202:205], v[20:23]
	v_mfma_f32_16x16x32_bf16 v[8:11], v[152:155], v[210:213], v[8:11]
	v_mfma_f32_16x16x32_bf16 v[4:7], v[160:163], v[210:213], v[4:7]
	s_setprio 0
	s_barrier
	s_branch .Lpe_join_431
	.p2align	6
